# v056 + loop-edge edit: attention rescale branch test shortened (lane-mask of the no-rescale flag derived with s_not_b64 instead of v_cndmask + v_cmp)
# baseline (speedup 1.0000x reference)
; DI float fexp2(float x) { return __builtin_amdgcn_exp2f(x); }
; DI void attn_unit(Ctx A_, LAS unsigned char* lds, int b, int h, int qb, float lam, int wave, int lane) {
;     ...
;             const bool resc = first || __any(tm > RESC_THR);
;             if (resc) {
;                 const float dl = first ? tm : fmaxf(tm, 0.f), f = fexp2(-dl); m = mi + dl; l *= f;
; #pragma unroll
;                 for (int i = 0; i < 16; ++i) { p0[i] -= dl; p1[i] -= dl; negm[i] = -m; }
;                 if (hh == 0) wsf[r] = f;
.LBB0_882:
	s_not_b64 s[6:7], s[22:23]
	s_andn2_b64 vcc, exec, s[22:23]
	s_cbranch_vccnz .LBB0_886
	v_max_f32_e32 v66, v174, v174
	v_max_f32_e32 v66, 0, v66
	v_cndmask_b32_e64 v68, v66, v174, s[4:5]
	v_exp_f32_e64 v67, -v68
	s_and_saveexec_b64 s[22:23], s[8:9]
	ds_write_b32 v217, v67
	s_or_b64 exec, exec, s[22:23]
	v_cndmask_b32_e64 v66, v219, 0, s[4:5]
	v_add_f32_e32 v219, v66, v68
	v_xor_b32_e32 v66, 0x80000000, v219
	v_sub_f32_e32 v113, v113, v68
	v_sub_f32_e32 v112, v112, v68
	v_sub_f32_e32 v111, v111, v68
	v_sub_f32_e32 v110, v110, v68
	v_sub_f32_e32 v109, v109, v68
	v_sub_f32_e32 v108, v108, v68
	v_sub_f32_e32 v107, v107, v68
	v_sub_f32_e32 v106, v106, v68
	v_sub_f32_e32 v105, v105, v68
	v_sub_f32_e32 v104, v104, v68
	v_sub_f32_e32 v103, v103, v68
	v_sub_f32_e32 v102, v102, v68
	v_sub_f32_e32 v101, v101, v68
	v_sub_f32_e32 v100, v100, v68
	v_sub_f32_e32 v99, v99, v68
	v_sub_f32_e32 v98, v98, v68
	v_sub_f32_e32 v97, v97, v68
	v_sub_f32_e32 v96, v96, v68
	v_sub_f32_e32 v95, v95, v68
	v_sub_f32_e32 v94, v94, v68
	v_sub_f32_e32 v93, v93, v68
	v_sub_f32_e32 v92, v92, v68
	v_sub_f32_e32 v91, v91, v68
	v_sub_f32_e32 v90, v90, v68
	v_sub_f32_e32 v89, v89, v68
	v_sub_f32_e32 v88, v88, v68
	v_sub_f32_e32 v87, v87, v68
	v_sub_f32_e32 v86, v86, v68
	v_sub_f32_e32 v85, v85, v68
	v_sub_f32_e32 v84, v84, v68
	v_sub_f32_e32 v83, v83, v68
	v_sub_f32_e32 v82, v82, v68
	v_mul_f32_e32 v218, v218, v67
	v_mov_b32_e32 v67, v66
	v_mov_b32_e32 v68, v66
	v_mov_b32_e32 v69, v66
	v_mov_b32_e32 v70, v66
	v_mov_b32_e32 v71, v66
	v_mov_b32_e32 v72, v66
	v_mov_b32_e32 v73, v66
	v_mov_b32_e32 v74, v66
	v_mov_b32_e32 v75, v66
	v_mov_b32_e32 v76, v66
	v_mov_b32_e32 v77, v66
	v_mov_b32_e32 v78, v66
	v_mov_b32_e32 v79, v66
	v_mov_b32_e32 v80, v66
	v_mov_b32_e32 v81, v66
